# FoX flash step: K-fragment and decay-bias LDS reads hoisted (issued up front into free VGPRs)
# speedup vs baseline: 1.0091x; 1.0091x over previous
.LBB0_479:
	s_mul_i32 s6, s20, 0x4800
	v_add_u32_e32 v147, s6, v109
	ds_read_b128 v[168:171], v147
	ds_read_b128 v[172:175], v147 offset:32
	ds_read_b128 v[176:179], v147 offset:64
	ds_read_b128 v[180:183], v147 offset:96
	ds_read_b128 v[184:187], v147 offset:4608
	ds_read_b128 v[188:191], v147 offset:4640
	ds_read_b128 v[192:195], v147 offset:4672
	ds_read_b128 v[196:199], v147 offset:4704
	s_lshl_b32 s17, s20, 8
	v_or_b32_e32 v153, s17, v108
	s_waitcnt lgkmcnt(7)
	v_mfma_f32_32x32x16_bf16 v[50:65], v[168:171], v[66:69], 0
	s_waitcnt lgkmcnt(6)
	v_mfma_f32_32x32x16_bf16 v[50:65], v[172:175], v[70:73], v[50:65]
	s_waitcnt lgkmcnt(5)
	v_mfma_f32_32x32x16_bf16 v[50:65], v[176:179], v[74:77], v[50:65]
	s_waitcnt lgkmcnt(4)
	v_mfma_f32_32x32x16_bf16 v[50:65], v[180:183], v[78:81], v[50:65]
	ds_read_b128 v[200:203], v153 offset:36864
	ds_read_b128 v[204:207], v153 offset:36896
	ds_read_b128 v[208:211], v153 offset:36928
	ds_read_b128 v[212:215], v153 offset:36960
	ds_read_b128 v[216:219], v153 offset:36992
	ds_read_b128 v[220:223], v153 offset:37024
	ds_read_b128 v[224:227], v153 offset:37056
	ds_read_b128 v[156:159], v153 offset:37088
	s_waitcnt lgkmcnt(11)
	v_mfma_f32_32x32x16_bf16 v[34:49], v[184:187], v[66:69], 0
	s_waitcnt lgkmcnt(10)
	v_mfma_f32_32x32x16_bf16 v[34:49], v[188:191], v[70:73], v[34:49]
	s_waitcnt lgkmcnt(9)
	v_mfma_f32_32x32x16_bf16 v[34:49], v[192:195], v[74:77], v[34:49]
	s_waitcnt lgkmcnt(8)
	v_mfma_f32_32x32x16_bf16 v[34:49], v[196:199], v[78:81], v[34:49]
	v_add_u32_e32 v126, 32, v146
	v_cmp_lt_i32_e32 vcc, 26, v126
	s_cmp_eq_u64 vcc, exec
	s_waitcnt lgkmcnt(0)
	v_pk_add_f32 v[128:129], v[124:125], v[200:201] neg_lo:[0,1] neg_hi:[0,1]
	v_pk_add_f32 v[130:131], v[124:125], v[202:203] neg_lo:[0,1] neg_hi:[0,1]
	v_pk_fma_f32 v[50:51], v[50:51], s[14:15], v[128:129] op_sel_hi:[1,0,1]
	v_pk_fma_f32 v[52:53], v[52:53], s[14:15], v[130:131] op_sel_hi:[1,0,1]
	v_pk_add_f32 v[128:129], v[124:125], v[204:205] neg_lo:[0,1] neg_hi:[0,1]
	v_pk_add_f32 v[130:131], v[124:125], v[206:207] neg_lo:[0,1] neg_hi:[0,1]
	v_pk_fma_f32 v[54:55], v[54:55], s[14:15], v[128:129] op_sel_hi:[1,0,1]
	v_pk_fma_f32 v[56:57], v[56:57], s[14:15], v[130:131] op_sel_hi:[1,0,1]
	v_pk_add_f32 v[128:129], v[124:125], v[208:209] neg_lo:[0,1] neg_hi:[0,1]
	v_pk_add_f32 v[130:131], v[124:125], v[210:211] neg_lo:[0,1] neg_hi:[0,1]
	v_pk_fma_f32 v[58:59], v[58:59], s[14:15], v[128:129] op_sel_hi:[1,0,1]
	v_pk_fma_f32 v[60:61], v[60:61], s[14:15], v[130:131] op_sel_hi:[1,0,1]
	v_pk_add_f32 v[128:129], v[124:125], v[212:213] neg_lo:[0,1] neg_hi:[0,1]
	v_pk_add_f32 v[130:131], v[124:125], v[214:215] neg_lo:[0,1] neg_hi:[0,1]
	v_pk_fma_f32 v[62:63], v[62:63], s[14:15], v[128:129] op_sel_hi:[1,0,1]
	v_pk_fma_f32 v[64:65], v[64:65], s[14:15], v[130:131] op_sel_hi:[1,0,1]
	s_cbranch_scc1 .LBB0_481
	v_cmp_lt_i32_e64 s[6:7], -1, v126
	v_cndmask_b32_e32 v65, v145, v65, vcc
	s_nop 0
	v_cndmask_b32_e64 v50, v145, v50, s[6:7]
	v_cmp_lt_i32_e64 s[6:7], 0, v126
	s_nop 1
	v_cndmask_b32_e64 v51, v145, v51, s[6:7]
	v_cmp_lt_i32_e64 s[6:7], 1, v126
	s_nop 1
	v_cndmask_b32_e64 v52, v145, v52, s[6:7]
	v_cmp_lt_i32_e64 s[6:7], 2, v126
	s_nop 1
	v_cndmask_b32_e64 v53, v145, v53, s[6:7]
	v_cmp_lt_i32_e64 s[6:7], 7, v126
	s_nop 1
	v_cndmask_b32_e64 v54, v145, v54, s[6:7]
	v_cmp_lt_i32_e64 s[6:7], 8, v126
	s_nop 1
	v_cndmask_b32_e64 v55, v145, v55, s[6:7]
	v_cmp_lt_i32_e64 s[6:7], 9, v126
	s_nop 1
	v_cndmask_b32_e64 v56, v145, v56, s[6:7]
	v_cmp_lt_i32_e64 s[6:7], 10, v126
	s_nop 1
	v_cndmask_b32_e64 v57, v145, v57, s[6:7]
	v_cmp_lt_i32_e64 s[6:7], 15, v126
	s_nop 1
	v_cndmask_b32_e64 v58, v145, v58, s[6:7]
	v_cmp_lt_i32_e64 s[6:7], 16, v126
	s_nop 1
	v_cndmask_b32_e64 v59, v145, v59, s[6:7]
	v_cmp_lt_i32_e64 s[6:7], 17, v126
	s_nop 1
	v_cndmask_b32_e64 v60, v145, v60, s[6:7]
	v_cmp_lt_i32_e64 s[6:7], 18, v126
	s_nop 1
	v_cndmask_b32_e64 v61, v145, v61, s[6:7]
	v_cmp_lt_i32_e64 s[6:7], 23, v126
	s_nop 1
	v_cndmask_b32_e64 v62, v145, v62, s[6:7]
	v_cmp_lt_i32_e64 s[6:7], 24, v126
	s_nop 1
	v_cndmask_b32_e64 v63, v145, v63, s[6:7]
	v_cmp_lt_i32_e64 s[6:7], 25, v126
	s_nop 1
	v_cndmask_b32_e64 v64, v145, v64, s[6:7]
.LBB0_481:
	v_cmp_lt_i32_e32 vcc, 26, v146
	s_cmp_eq_u64 vcc, exec
	v_pk_add_f32 v[148:149], v[124:125], v[216:217] neg_lo:[0,1] neg_hi:[0,1]
	v_pk_add_f32 v[150:151], v[124:125], v[218:219] neg_lo:[0,1] neg_hi:[0,1]
	v_pk_fma_f32 v[132:133], v[34:35], s[14:15], v[148:149] op_sel_hi:[1,0,1]
	v_pk_fma_f32 v[130:131], v[36:37], s[14:15], v[150:151] op_sel_hi:[1,0,1]
	v_pk_add_f32 v[148:149], v[124:125], v[220:221] neg_lo:[0,1] neg_hi:[0,1]
	v_pk_add_f32 v[150:151], v[124:125], v[222:223] neg_lo:[0,1] neg_hi:[0,1]
	v_pk_fma_f32 v[128:129], v[38:39], s[14:15], v[148:149] op_sel_hi:[1,0,1]
	v_pk_fma_f32 v[126:127], v[40:41], s[14:15], v[150:151] op_sel_hi:[1,0,1]
	v_pk_add_f32 v[148:149], v[124:125], v[224:225] neg_lo:[0,1] neg_hi:[0,1]
	v_pk_add_f32 v[150:151], v[124:125], v[226:227] neg_lo:[0,1] neg_hi:[0,1]
	v_pk_fma_f32 v[40:41], v[42:43], s[14:15], v[148:149] op_sel_hi:[1,0,1]
	v_pk_fma_f32 v[36:37], v[44:45], s[14:15], v[150:151] op_sel_hi:[1,0,1]
	v_pk_add_f32 v[148:149], v[124:125], v[156:157] neg_lo:[0,1] neg_hi:[0,1]
	v_pk_add_f32 v[150:151], v[124:125], v[158:159] neg_lo:[0,1] neg_hi:[0,1]
	v_pk_fma_f32 v[34:35], v[46:47], s[14:15], v[148:149] op_sel_hi:[1,0,1]
	v_pk_fma_f32 v[38:39], v[48:49], s[14:15], v[150:151] op_sel_hi:[1,0,1]
	s_cbranch_scc1 .LBB0_483
	v_cmp_lt_i32_e64 s[6:7], -1, v146
	v_cndmask_b32_e32 v39, v145, v39, vcc
	s_nop 0
	v_cndmask_b32_e64 v132, v145, v132, s[6:7]
	v_cmp_lt_i32_e64 s[6:7], 0, v146
	s_nop 1
	v_cndmask_b32_e64 v133, v145, v133, s[6:7]
	v_cmp_lt_i32_e64 s[6:7], 1, v146
	s_nop 1
	v_cndmask_b32_e64 v130, v145, v130, s[6:7]
	v_cmp_lt_i32_e64 s[6:7], 2, v146
	s_nop 1
	v_cndmask_b32_e64 v131, v145, v131, s[6:7]
	v_cmp_lt_i32_e64 s[6:7], 7, v146
	s_nop 1
	v_cndmask_b32_e64 v128, v145, v128, s[6:7]
	v_cmp_lt_i32_e64 s[6:7], 8, v146
	s_nop 1
	v_cndmask_b32_e64 v129, v145, v129, s[6:7]
	v_cmp_lt_i32_e64 s[6:7], 9, v146
	s_nop 1
	v_cndmask_b32_e64 v126, v145, v126, s[6:7]
	v_cmp_lt_i32_e64 s[6:7], 10, v146
	s_nop 1
	v_cndmask_b32_e64 v127, v145, v127, s[6:7]
	v_cmp_lt_i32_e64 s[6:7], 15, v146
	s_nop 1
	v_cndmask_b32_e64 v40, v145, v40, s[6:7]
	v_cmp_lt_i32_e64 s[6:7], 16, v146
	s_nop 1
	v_cndmask_b32_e64 v41, v145, v41, s[6:7]
	v_cmp_lt_i32_e64 s[6:7], 17, v146
	s_nop 1
	v_cndmask_b32_e64 v36, v145, v36, s[6:7]
	v_cmp_lt_i32_e64 s[6:7], 18, v146
	s_nop 1
	v_cndmask_b32_e64 v37, v145, v37, s[6:7]
	v_cmp_lt_i32_e64 s[6:7], 23, v146
	s_nop 1
	v_cndmask_b32_e64 v34, v145, v34, s[6:7]
	v_cmp_lt_i32_e64 s[6:7], 24, v146
	s_nop 1
	v_cndmask_b32_e64 v35, v145, v35, s[6:7]
	v_cmp_lt_i32_e64 s[6:7], 25, v146
	s_nop 1
	v_cndmask_b32_e64 v38, v145, v38, s[6:7]
